# baseline (speedup 1.0000x reference)
; __device__ __forceinline__ void gemm_phase(const Params& p, int kind, int layer, u16* shm, const int wv) {
;     ...
;   auto epif = [&](int pn, int& ccol) -> EpiD {
;     EpiD e = ep; ccol = pn * BM;
;     if (kind == G_PROJ0) {
;       const int sec = pn >> 2, cin = (pn & 3) * 256;
;       e.mode = EP_BF16;
;       if (pn == 32)      { e.mode = EP_F32; e.dst = p.ws + O_GAB * MiB; e.ld = 16; e.ncols = 16; ccol = 0; }
;       else if (sec == 0) { e.dst = p.ws + O_QA * MiB; e.ld = 1024; ccol = cin; }
;       else if (sec == 1) { e.mode = EP_F32; e.dst = (char*)p.out + 64 * MiB; e.ld = 1024; ccol = cin; }
;       else if (sec == 2) { e.dst = p.ws + O_VA * MiB; e.ld = 1024; ccol = cin; }
;       else if (sec == 3) { e.dst = p.out; e.ld = 2048; ccol = cin; }
;       else if (sec == 7) { e.dst = p.out; e.ld = 2048; ccol = 1024 + cin; }
;       else               { e.dst = p.ws + O_GQKV * MiB; e.ld = 3072; ccol = (sec - 4) * 1024 + cin; }
.LBB0_200:
	s_load_dwordx2 vcc, s[62:63], 0x88
	s_lshl_b32 s10, s25, 10
	s_or_b32 s10, s10, s24
	s_add_i32 s22, s10, 0xfffff000
	s_mov_b64 s[10:11], 0xc000000
	s_movk_i32 s83, 0xc00
	s_waitcnt lgkmcnt(0)
	v_mov_b32_e32 v146, vcc_lo
	v_mov_b32_e32 v147, vcc_hi
	v_lshl_add_u64 v[146:147], v[146:147], 0, s[10:11]
	s_mov_b32 s84, 0
	s_cbranch_execz .LBB0_209
	s_branch .LBB0_210

; __device__ __forceinline__ void gemm_phase(const Params& p, int kind, int layer, u16* shm, const int wv) {
;     ...
;       else if (sec == 0) { e.dst = p.ws + O_QA * MiB; e.ld = 1024; ccol = cin; }
;       else if (sec == 1) { e.mode = EP_F32; e.dst = (char*)p.out + 64 * MiB; e.ld = 1024; ccol = cin; }
;       else if (sec == 2) { e.dst = p.ws + O_VA * MiB; e.ld = 1024; ccol = cin; }
;       else if (sec == 3) { e.dst = p.out; e.ld = 2048; ccol = cin; }
;       else if (sec == 7) { e.dst = p.out; e.ld = 2048; ccol = 1024 + cin; }
;       else               { e.dst = p.ws + O_GQKV * MiB; e.ld = 3072; ccol = (sec - 4) * 1024 + cin; }
.LBB0_202:
	s_movk_i32 s83, 0x800
	s_and_b64 vcc, exec, s[12:13]
	s_cbranch_vccz .LBB0_199
	s_cmp_gt_i32 s25, 1
	s_mov_b64 s[8:9], -1
	s_cbranch_scc0 .LBB0_205
	s_load_dwordx2 vcc, s[62:63], 0x88
	s_mov_b64 s[8:9], 0xa000000
	s_waitcnt lgkmcnt(0)
	v_mov_b32_e32 v146, vcc_lo
	v_mov_b32_e32 v147, vcc_hi
	v_lshl_add_u64 v[146:147], v[146:147], 0, s[8:9]
	s_mov_b64 s[8:9], 0

; __device__ __forceinline__ void gemm_phase(const Params& p, int kind, int layer, u16* shm, const int wv) {
;     ...
;       else if (sec == 1) { e.mode = EP_F32; e.dst = (char*)p.out + 64 * MiB; e.ld = 1024; ccol = cin; }
.LBB0_209:
	s_load_dwordx2 vcc, s[62:63], 0x80
	s_mov_b32 s84, 1
	s_movk_i32 s83, 0x400
	s_mov_b32 s22, s24
	s_waitcnt lgkmcnt(0)
	v_mov_b32_e32 v146, vcc_lo
	v_mov_b32_e32 v147, vcc_hi
	v_lshl_add_u64 v[146:147], v[146:147], 0, s[44:45]

; __device__ __forceinline__ void gemm_phase(const Params& p, int kind, int layer, u16* shm, const int wv) {
;     ...
;       else if (sec == 0) { e.dst = p.ws + O_QA * MiB; e.ld = 1024; ccol = cin; }
.LBB0_211:
	s_and_b64 vcc, exec, s[8:9]
	s_cbranch_vccz .LBB0_213
	s_load_dwordx2 vcc, s[62:63], 0x88
	s_mov_b64 s[8:9], 0x8000000
	s_mov_b32 s84, 0
	s_movk_i32 s83, 0x400
	s_mov_b32 s22, s24
	s_waitcnt lgkmcnt(0)
	v_mov_b32_e32 v146, vcc_lo
	v_mov_b32_e32 v147, vcc_hi
	v_lshl_add_u64 v[146:147], v[146:147], 0, s[8:9]

; __device__ __forceinline__ void gemm_phase(const Params& p, int kind, int layer, u16* shm, const int wv) {
;     ...
;       if (pn == 32)      { e.mode = EP_F32; e.dst = p.ws + O_GAB * MiB; e.ld = 16; e.ncols = 16; ccol = 0; }
.LBB0_214:
	s_andn2_b64 vcc, exec, s[8:9]
	s_cbranch_vccnz .LBB0_216
	s_load_dwordx2 vcc, s[62:63], 0x88
	s_mov_b64 s[8:9], 0x12000000
	s_mov_b32 s22, 0
	s_mov_b32 s84, 1
	s_mov_b32 s28, 16
	s_mov_b32 s83, 16
	s_waitcnt lgkmcnt(0)
	v_mov_b32_e32 v146, vcc_lo
	v_mov_b32_e32 v147, vcc_hi
	v_lshl_add_u64 v[146:147], v[146:147], 0, s[8:9]
